# NA band tiles: also skip the QK^T MFMAs of key blocks outside the wave's window (masked to -inf anyway); context tiles unchanged
# speedup vs baseline: 1.0027x; 1.0012x over previous
.LBB0_1021:
	s_bitcmp1_b32 s0, 0
	s_cselect_b32 s0, 0x8800, 0
	s_add_i32 s87, s0, 0
	s_cmp_ge_i32 s5, s28
	s_cbranch_scc1 .LBB0_1107
	s_cmp_lt_i32 s5, s7
	s_cselect_b64 s[0:1], -1, 0
	s_cmp_ge_i32 s5, s7
	s_cselect_b64 s[2:3], -1, 0
	s_add_i32 s20, s4, s5
	s_add_i32 s20, s20, -4
	v_cmp_ge_u32_e64 s[58:59], s20, v200
	v_cmp_lt_u32_e32 vcc, s20, v201
	s_and_b64 s[56:57], s[58:59], vcc
	s_or_b64 s[56:57], s[2:3], s[56:57]
	s_and_saveexec_b64 s[2:3], s[56:57]
	s_cbranch_execz .LBB0_1102
	v_add_u32_e32 v0, s87, v202
	v_add_u32_e32 v76, v0, v203
	v_add_u32_e32 v0, v0, v204
	ds_read_b128 v[108:111], v76
	ds_read_b128 v[112:115], v76 offset:2048
	ds_read_b128 v[116:119], v76 offset:4096
	ds_read_b128 v[120:123], v76 offset:6144
	ds_read_b128 v[124:127], v0
	ds_read_b128 v[128:131], v0 offset:2048
	ds_read_b128 v[132:135], v0 offset:4096
	ds_read_b128 v[136:139], v0 offset:6144
	v_add3_u32 v0, s87, v199, v205
	v_add_u32_e32 v92, 0x2000, v0
	v_add_u32_e32 v96, 0x2800, v0
	v_add_u32_e32 v100, 0x3000, v0
	v_add_u32_e32 v0, 0x3800, v0
	ds_read2_b64 v[76:79], v92 offset1:4
	ds_read2_b64 v[80:83], v96 offset0:32 offset1:36
	ds_read2_b64 v[84:87], v100 offset0:64 offset1:68
	ds_read2_b64 v[88:91], v0 offset0:96 offset1:100
	ds_read2_b64 v[92:95], v92 offset0:8 offset1:12
	ds_read2_b64 v[96:99], v96 offset0:40 offset1:44
	ds_read2_b64 v[100:103], v100 offset0:72 offset1:76
	ds_read2_b64 v[104:107], v0 offset0:104 offset1:108
	v_readfirstlane_b32 s56, v166
	s_bfe_u32 s56, s56, 0x20006
	s_lshl_b32 s56, s56, 2
	s_lshr_b32 s56, 0xce73, s56
	s_cmp_lg_u64 s[0:1], 0
	s_cselect_b32 s56, s56, 15
	s_waitcnt lgkmcnt(14)
	s_setprio 1
	s_bitcmp0_b32 s56, 0
	s_cbranch_scc1 .Lnm0_0
	v_mfma_f32_16x16x32_bf16 v[140:143], v[108:111], v[4:7], 0
	v_mfma_f32_16x16x32_bf16 v[108:111], v[108:111], v[12:15], 0
.Lnm0_0:
	s_bitcmp0_b32 s56, 1
	s_cbranch_scc1 .Lnm0_1
	v_mfma_f32_16x16x32_bf16 v[144:147], v[112:115], v[4:7], 0
	v_mfma_f32_16x16x32_bf16 v[112:115], v[112:115], v[12:15], 0
.Lnm0_1:
	s_waitcnt lgkmcnt(13)
	s_bitcmp0_b32 s56, 2
	s_cbranch_scc1 .Lnm0_2
	v_mfma_f32_16x16x32_bf16 v[148:151], v[116:119], v[4:7], 0
	v_mfma_f32_16x16x32_bf16 v[116:119], v[116:119], v[12:15], 0
.Lnm0_2:
	s_waitcnt lgkmcnt(12)
	s_bitcmp0_b32 s56, 3
	s_cbranch_scc1 .Lnm0_3
	v_mfma_f32_16x16x32_bf16 v[152:155], v[120:123], v[4:7], 0
	v_mfma_f32_16x16x32_bf16 v[120:123], v[120:123], v[12:15], 0
.Lnm0_3:
	s_waitcnt lgkmcnt(11)
	s_bitcmp0_b32 s56, 0
	s_cbranch_scc1 .Lnm0_4
	v_mfma_f32_16x16x32_bf16 v[140:143], v[124:127], v[8:11], v[140:143]
	v_mfma_f32_16x16x32_bf16 v[108:111], v[124:127], v[16:19], v[108:111]
.Lnm0_4:
	s_waitcnt lgkmcnt(10)
	s_bitcmp0_b32 s56, 1
	s_cbranch_scc1 .Lnm0_5
	v_mfma_f32_16x16x32_bf16 v[144:147], v[128:131], v[8:11], v[144:147]
	v_mfma_f32_16x16x32_bf16 v[112:115], v[128:131], v[16:19], v[112:115]
.Lnm0_5:
	s_waitcnt lgkmcnt(9)
	s_bitcmp0_b32 s56, 2
	s_cbranch_scc1 .Lnm0_6
	v_mfma_f32_16x16x32_bf16 v[148:151], v[132:135], v[8:11], v[148:151]
	v_mfma_f32_16x16x32_bf16 v[116:119], v[132:135], v[16:19], v[116:119]
.Lnm0_6:
	s_waitcnt lgkmcnt(8)
	s_bitcmp0_b32 s56, 3
	s_cbranch_scc1 .Lnm0_7
	v_mfma_f32_16x16x32_bf16 v[152:155], v[136:139], v[8:11], v[152:155]
	v_mfma_f32_16x16x32_bf16 v[120:123], v[136:139], v[16:19], v[120:123]
.Lnm0_7:
	s_setprio 0
	v_cndmask_b32_e64 v0, 0, 1, s[0:1]
	v_cmp_ne_u32_e64 s[56:57], 1, v0
	s_andn2_b64 vcc, exec, s[0:1]
	s_mov_b64 s[66:67], -1
	s_cbranch_vccnz .LBB0_1189
	v_add3_u32 v0, v225, s5, -4
	v_max_i32_e32 v0, -7, v0
	v_add_u32_e32 v0, 7, v0
	v_readlane_b32 s65, v254, 35
	v_cmp_lt_u32_e32 vcc, s20, v206
	v_min_u32_e32 v0, 14, v0
	v_mov_b32_e32 v124, s65
	s_movk_i32 s65, 0x7c
	v_mad_u32_u24 v0, v0, s65, v124
	v_lshl_add_u32 v124, v207, 2, v0
	v_lshl_add_u32 v125, v208, 2, v0
	v_lshl_add_u32 v126, v209, 2, v0
	v_lshl_add_u32 v127, v210, 2, v0
	v_lshl_add_u32 v128, v211, 2, v0
	v_lshl_add_u32 v129, v212, 2, v0
	v_lshl_add_u32 v130, v213, 2, v0
	v_lshl_add_u32 v131, v214, 2, v0
	v_lshl_add_u32 v132, v215, 2, v0
	v_lshl_add_u32 v133, v216, 2, v0
	v_lshl_add_u32 v134, v217, 2, v0
	v_lshl_add_u32 v135, v218, 2, v0
	v_lshl_add_u32 v136, v219, 2, v0
	v_lshl_add_u32 v137, v220, 2, v0
	v_lshl_add_u32 v138, v221, 2, v0
	v_lshl_add_u32 v139, v222, 2, v0
	ds_read_b32 v124, v124 offset:60
	ds_read_b32 v125, v125 offset:60
	ds_read_b32 v126, v126 offset:60
	ds_read_b32 v127, v127 offset:60
	ds_read_b32 v128, v128
	ds_read_b32 v129, v129
	ds_read_b32 v130, v130
	ds_read_b32 v131, v131
	ds_read_b32 v132, v132
	ds_read_b32 v133, v133
	ds_read_b32 v134, v134
	ds_read_b32 v135, v135
	ds_read_b32 v136, v136
	ds_read_b32 v137, v137
	ds_read_b32 v138, v138
	ds_read_b32 v139, v139
	s_and_b64 s[58:59], s[58:59], vcc
	v_mov_b32_e32 v0, 0xff800000
	s_and_b64 s[66:67], s[40:41], s[58:59]
	s_waitcnt lgkmcnt(0)
	v_fmac_f32_e32 v124, 0x3e38aa3b, v140
	v_fmac_f32_e32 v125, 0x3e38aa3b, v141
	v_fmac_f32_e32 v126, 0x3e38aa3b, v142
	v_fmac_f32_e32 v127, 0x3e38aa3b, v143
	v_fmac_f32_e32 v128, 0x3e38aa3b, v144
	v_fmac_f32_e32 v129, 0x3e38aa3b, v145
	v_fmac_f32_e32 v130, 0x3e38aa3b, v146
	v_fmac_f32_e32 v131, 0x3e38aa3b, v147
	v_fmac_f32_e32 v132, 0x3e38aa3b, v148
	v_fmac_f32_e32 v133, 0x3e38aa3b, v149
	v_fmac_f32_e32 v134, 0x3e38aa3b, v150
	v_fmac_f32_e32 v135, 0x3e38aa3b, v151
	v_fmac_f32_e32 v136, 0x3e38aa3b, v152
	v_fmac_f32_e32 v137, 0x3e38aa3b, v153
	v_fmac_f32_e32 v138, 0x3e38aa3b, v154
	v_fmac_f32_e32 v139, 0x3e38aa3b, v155
	s_and_b64 s[82:83], s[42:43], s[58:59]
	v_cndmask_b32_e64 v124, v0, v124, s[66:67]
	s_and_b64 s[66:67], s[44:45], s[58:59]
	v_cndmask_b32_e64 v125, v0, v125, s[82:83]
	s_and_b64 s[82:83], s[46:47], s[58:59]
	v_cndmask_b32_e64 v126, v0, v126, s[66:67]
	s_and_b64 s[66:67], s[90:91], s[58:59]
	v_cndmask_b32_e64 v127, v0, v127, s[82:83]
	s_and_b64 s[82:83], s[8:9], s[58:59]
	v_cndmask_b32_e64 v128, v0, v128, s[66:67]
	s_and_b64 s[66:67], s[88:89], s[58:59]
	v_cndmask_b32_e64 v129, v0, v129, s[82:83]
	s_and_b64 s[82:83], s[94:95], s[58:59]
	v_cndmask_b32_e64 v130, v0, v130, s[66:67]
	s_and_b64 s[66:67], s[96:97], s[58:59]
	v_cndmask_b32_e64 v131, v0, v131, s[82:83]
	s_and_b64 s[82:83], s[84:85], s[58:59]
	v_cndmask_b32_e64 v132, v0, v132, s[66:67]
	s_and_b64 s[66:67], s[18:19], s[58:59]
	v_cndmask_b32_e64 v133, v0, v133, s[82:83]
	s_and_b64 s[82:83], s[62:63], s[58:59]
	v_cndmask_b32_e64 v134, v0, v134, s[66:67]
	s_and_b64 s[66:67], s[48:49], s[58:59]
	v_cndmask_b32_e64 v135, v0, v135, s[82:83]
	s_and_b64 s[82:83], s[50:51], s[58:59]
	v_cndmask_b32_e64 v136, v0, v136, s[66:67]
	s_and_b64 s[66:67], s[52:53], s[58:59]
	v_cndmask_b32_e64 v137, v0, v137, s[82:83]
	s_and_b64 s[82:83], s[54:55], s[58:59]
	v_cndmask_b32_e64 v138, v0, v138, s[66:67]
	s_nop 0
	v_cndmask_b32_e64 v139, v0, v139, s[82:83]
	v_max3_f32 v0, v2, v124, v125
	v_max3_f32 v0, v0, v126, v127
	v_max3_f32 v0, v0, v128, v129
	v_max3_f32 v0, v0, v130, v131
	v_max3_f32 v0, v0, v132, v133
	v_max3_f32 v0, v0, v134, v135
	v_max3_f32 v0, v0, v136, v137
	v_max3_f32 v0, v0, v138, v139

.LBB0_1108:
	s_cmp_lt_i32 s2, s7
	s_cselect_b64 s[0:1], -1, 0
	s_cmp_ge_i32 s2, s7
	s_cselect_b64 s[2:3], -1, 0
	s_add_i32 s20, s4, s5
	s_add_i32 s20, s20, -3
	v_cmp_ge_u32_e64 s[58:59], s20, v200
	v_cmp_lt_u32_e32 vcc, s20, v201
	s_and_b64 s[56:57], s[58:59], vcc
	s_or_b64 s[56:57], s[2:3], s[56:57]
	s_and_saveexec_b64 s[2:3], s[56:57]
	s_cbranch_execz .LBB0_1188
	v_add_u32_e32 v0, s87, v202
	v_add_u32_e32 v76, v0, v203
	v_add_u32_e32 v0, v0, v204
	ds_read_b128 v[108:111], v76 offset:17408
	ds_read_b128 v[112:115], v76 offset:19456
	ds_read_b128 v[116:119], v76 offset:21504
	ds_read_b128 v[120:123], v76 offset:23552
	ds_read_b128 v[124:127], v0 offset:17408
	ds_read_b128 v[128:131], v0 offset:19456
	ds_read_b128 v[132:135], v0 offset:21504
	ds_read_b128 v[136:139], v0 offset:23552
	v_add3_u32 v0, s87, v199, v205
	v_add_u32_e32 v92, 0x6000, v0
	v_add_u32_e32 v96, 0x6800, v0
	v_add_u32_e32 v100, 0x7000, v0
	v_add_u32_e32 v0, 0x7800, v0
	ds_read2_b64 v[76:79], v92 offset0:128 offset1:132
	ds_read2_b64 v[80:83], v96 offset0:160 offset1:164
	ds_read2_b64 v[84:87], v100 offset0:192 offset1:196
	ds_read2_b64 v[88:91], v0 offset0:224 offset1:228
	ds_read2_b64 v[92:95], v92 offset0:136 offset1:140
	ds_read2_b64 v[96:99], v96 offset0:168 offset1:172
	ds_read2_b64 v[100:103], v100 offset0:200 offset1:204
	ds_read2_b64 v[104:107], v0 offset0:232 offset1:236
	v_readfirstlane_b32 s56, v166
	s_bfe_u32 s56, s56, 0x20006
	s_lshl_b32 s56, s56, 2
	s_lshr_b32 s56, 0xce73, s56
	s_cmp_lg_u64 s[0:1], 0
	s_cselect_b32 s56, s56, 15
	s_waitcnt lgkmcnt(14)
	s_setprio 1
	s_bitcmp0_b32 s56, 0
	s_cbranch_scc1 .Lnm1_0
	v_mfma_f32_16x16x32_bf16 v[140:143], v[108:111], v[4:7], 0
	v_mfma_f32_16x16x32_bf16 v[108:111], v[108:111], v[12:15], 0

.Lnm1_7:
	s_setprio 0
	v_cndmask_b32_e64 v0, 0, 1, s[0:1]
	v_cmp_ne_u32_e64 s[56:57], 1, v0
	s_andn2_b64 vcc, exec, s[0:1]
	s_mov_b64 s[0:1], -1
	s_cbranch_vccnz .LBB0_1195
	v_add3_u32 v0, v225, s5, -3
	v_max_i32_e32 v0, -7, v0
	v_add_u32_e32 v0, 7, v0
	v_readlane_b32 s0, v254, 35
	v_min_u32_e32 v0, 14, v0
	v_cmp_lt_u32_e32 vcc, s20, v206
	v_mov_b32_e32 v124, s0
	s_movk_i32 s0, 0x7c
	v_mad_u32_u24 v0, v0, s0, v124
	v_lshl_add_u32 v124, v207, 2, v0
	v_lshl_add_u32 v125, v208, 2, v0
	v_lshl_add_u32 v126, v209, 2, v0
	v_lshl_add_u32 v127, v210, 2, v0
	v_lshl_add_u32 v128, v211, 2, v0
	v_lshl_add_u32 v129, v212, 2, v0
	v_lshl_add_u32 v130, v213, 2, v0
	v_lshl_add_u32 v131, v214, 2, v0
	v_lshl_add_u32 v132, v215, 2, v0
	v_lshl_add_u32 v133, v216, 2, v0
	v_lshl_add_u32 v134, v217, 2, v0
	v_lshl_add_u32 v135, v218, 2, v0
	v_lshl_add_u32 v136, v219, 2, v0
	v_lshl_add_u32 v137, v220, 2, v0
	v_lshl_add_u32 v138, v221, 2, v0
	v_lshl_add_u32 v139, v222, 2, v0
	ds_read_b32 v124, v124 offset:60
	ds_read_b32 v125, v125 offset:60
	ds_read_b32 v126, v126 offset:60
	ds_read_b32 v127, v127 offset:60
	ds_read_b32 v128, v128
	ds_read_b32 v129, v129
	ds_read_b32 v130, v130
	ds_read_b32 v131, v131
	ds_read_b32 v132, v132
	ds_read_b32 v133, v133
	ds_read_b32 v134, v134
	ds_read_b32 v135, v135
	ds_read_b32 v136, v136
	ds_read_b32 v137, v137
	ds_read_b32 v138, v138
	ds_read_b32 v139, v139
	s_and_b64 s[58:59], s[58:59], vcc
	v_mov_b32_e32 v0, 0xff800000
	s_and_b64 s[0:1], s[40:41], s[58:59]
	s_waitcnt lgkmcnt(0)
	v_fmac_f32_e32 v124, 0x3e38aa3b, v140
	v_fmac_f32_e32 v125, 0x3e38aa3b, v141
	v_fmac_f32_e32 v126, 0x3e38aa3b, v142
	v_fmac_f32_e32 v127, 0x3e38aa3b, v143
	v_fmac_f32_e32 v128, 0x3e38aa3b, v144
	v_fmac_f32_e32 v129, 0x3e38aa3b, v145
	v_fmac_f32_e32 v130, 0x3e38aa3b, v146
	v_fmac_f32_e32 v131, 0x3e38aa3b, v147
	v_fmac_f32_e32 v132, 0x3e38aa3b, v148
	v_fmac_f32_e32 v133, 0x3e38aa3b, v149
	v_fmac_f32_e32 v134, 0x3e38aa3b, v150
	v_fmac_f32_e32 v135, 0x3e38aa3b, v151
	v_fmac_f32_e32 v136, 0x3e38aa3b, v152
	v_fmac_f32_e32 v137, 0x3e38aa3b, v153
	v_fmac_f32_e32 v138, 0x3e38aa3b, v154
	v_fmac_f32_e32 v139, 0x3e38aa3b, v155
	s_and_b64 s[66:67], s[42:43], s[58:59]
	v_cndmask_b32_e64 v124, v0, v124, s[0:1]
	s_and_b64 s[0:1], s[44:45], s[58:59]
	v_cndmask_b32_e64 v125, v0, v125, s[66:67]
	s_and_b64 s[66:67], s[46:47], s[58:59]
	v_cndmask_b32_e64 v126, v0, v126, s[0:1]
	s_and_b64 s[0:1], s[90:91], s[58:59]
	v_cndmask_b32_e64 v127, v0, v127, s[66:67]
	s_and_b64 s[66:67], s[8:9], s[58:59]
	v_cndmask_b32_e64 v128, v0, v128, s[0:1]
	s_and_b64 s[0:1], s[88:89], s[58:59]
	v_cndmask_b32_e64 v129, v0, v129, s[66:67]
	s_and_b64 s[66:67], s[94:95], s[58:59]
	v_cndmask_b32_e64 v130, v0, v130, s[0:1]
	s_and_b64 s[0:1], s[96:97], s[58:59]
	v_cndmask_b32_e64 v131, v0, v131, s[66:67]
	s_and_b64 s[66:67], s[84:85], s[58:59]
	v_cndmask_b32_e64 v132, v0, v132, s[0:1]
	s_and_b64 s[0:1], s[18:19], s[58:59]
	v_cndmask_b32_e64 v133, v0, v133, s[66:67]
	s_and_b64 s[66:67], s[62:63], s[58:59]
	v_cndmask_b32_e64 v134, v0, v134, s[0:1]
	s_and_b64 s[0:1], s[48:49], s[58:59]
	v_cndmask_b32_e64 v135, v0, v135, s[66:67]
	s_and_b64 s[66:67], s[50:51], s[58:59]
	v_cndmask_b32_e64 v136, v0, v136, s[0:1]
	s_and_b64 s[0:1], s[52:53], s[58:59]
	v_cndmask_b32_e64 v137, v0, v137, s[66:67]
	s_and_b64 s[66:67], s[54:55], s[58:59]
	v_cndmask_b32_e64 v138, v0, v138, s[0:1]
	s_nop 0
	v_cndmask_b32_e64 v139, v0, v139, s[66:67]
	v_max3_f32 v0, v2, v124, v125
	v_max3_f32 v0, v0, v126, v127
	v_max3_f32 v0, v0, v128, v129
	v_max3_f32 v0, v0, v130, v131
	v_max3_f32 v0, v0, v132, v133
	v_max3_f32 v0, v0, v134, v135
	v_max3_f32 v0, v0, v136, v137
	v_max3_f32 v0, v0, v138, v139
